# diff-attention tile loop: K/V staging ds_writes wait only for the tile loaded one step earlier (vmcnt 7..4) when this step issued its own loads, with a vmcnt(0) drain at loop exit; stacked on queue pe
# speedup vs baseline: 1.0075x; 1.0055x over previous
; #define LAS __attribute__((address_space(3)))
; template <int MODE> ...
;     ...
;     float mrun = NEG, lsum = 0.f;
;     if (MODE == 1) { mrun = sink2w + sl2w * (float)(wq0 + r32 - q0); lsum = hi == 0 ? 1.f : 0.f; }
;     const bool dovote = (MODE != 0) || (sl2 * (float)(q0 + ROWS) >= 150.0f);
;     const bool fixed = REV && !__any(qkb >= 66.0f);
;     if (MODE == 0 && fixed) mrun = sl2 * (float)(wq0 + r32 - q0) + qkb - 20.0f;
;     f32x16 O[NC];
; #pragma unroll
;     for (int c = 0; c < NC; ++c)
; #pragma unroll
;         for (int r = 0; r < 16; ++r) O[c][r] = 0.f;
;     LAS float* wsf = (LAS float*)(lds + WS_OFF) + wid * 32;
;     const int nt = t_hi - t_lo;
;     LAS int* vote = (LAS int*)(lds + VOTE_OFF);
;     bool wdone = false;
.LBB0_267:
	s_add_i32 s12, s2, -2
	s_cmp_lt_u32 s12, s20
	s_cselect_b64 s[10:11], -1, 0
	s_cmp_ge_u32 s12, s20
	s_cbranch_scc1 .LBB0_270
	v_add_u32_e32 v0, 0xcc00, v212
	s_and_b64 vcc, exec, s[8:9]
	s_cbranch_vccz .Lvm_a_old
	s_waitcnt vmcnt(7)
	ds_write_b128 v210, v[130:133] offset:17408
	s_waitcnt vmcnt(6)
	ds_write_b128 v211, v[134:137] offset:17408
	s_waitcnt vmcnt(5)
	ds_write2_b64 v0, v[138:139], v[140:141] offset1:1
	v_add_u32_e32 v0, 0xcc00, v214
	s_andn2_b64 vcc, exec, s[4:5]
	s_waitcnt vmcnt(4)
	ds_write2_b64 v0, v[142:143], v[144:145] offset1:1
	s_cbranch_vccnz .LBB0_270
	s_branch .Lvm_a_join
.Lvm_a_old:
	s_waitcnt vmcnt(3)
	ds_write_b128 v210, v[130:133] offset:17408
	s_waitcnt vmcnt(2)
	ds_write_b128 v211, v[134:137] offset:17408
	s_waitcnt vmcnt(1)
	ds_write2_b64 v0, v[138:139], v[140:141] offset1:1
	v_add_u32_e32 v0, 0xcc00, v214
	s_andn2_b64 vcc, exec, s[4:5]
	s_waitcnt vmcnt(0)
	ds_write2_b64 v0, v[142:143], v[144:145] offset1:1
	s_cbranch_vccnz .LBB0_270
.Lvm_a_join:
	v_add_u32_e32 v0, s29, v209
	v_cvt_f32_i32_e32 v0, v0
	v_mul_f32_e32 v0, v208, v0
	ds_write_b32 v234, v0 offset:256

; #define LAS __attribute__((address_space(3)))
; template <int MODE> ...
;     ...
;     float mrun = NEG, lsum = 0.f;
;     if (MODE == 1) { mrun = sink2w + sl2w * (float)(wq0 + r32 - q0); lsum = hi == 0 ? 1.f : 0.f; }
;     const bool dovote = (MODE != 0) || (sl2 * (float)(q0 + ROWS) >= 150.0f);
;     const bool fixed = REV && !__any(qkb >= 66.0f);
;     if (MODE == 0 && fixed) mrun = sl2 * (float)(wq0 + r32 - q0) + qkb - 20.0f;
;     f32x16 O[NC];
; #pragma unroll
;     for (int c = 0; c < NC; ++c)
; #pragma unroll
;         for (int r = 0; r < 16; ++r) O[c][r] = 0.f;
;     LAS float* wsf = (LAS float*)(lds + WS_OFF) + wid * 32;
;     const int nt = t_hi - t_lo;
;     LAS int* vote = (LAS int*)(lds + VOTE_OFF);
;     bool wdone = false;
.LBB0_294:
	s_andn2_b64 vcc, exec, s[8:9]
	s_cbranch_vccnz .LBB0_297
	s_andn2_b64 vcc, exec, s[4:5]
	s_cmp_lt_u32 s2, s20
	s_cbranch_scc0 .Lvm_b_old
	s_waitcnt vmcnt(7)
	ds_write_b128 v210, v[114:117]
	s_waitcnt vmcnt(6)
	ds_write_b128 v211, v[118:121]
	s_waitcnt vmcnt(5)
	ds_write2_b64 v213, v[122:123], v[124:125] offset1:1
	s_waitcnt vmcnt(4)
	ds_write2_b64 v215, v[126:127], v[128:129] offset1:1
	s_cbranch_vccnz .LBB0_297
	s_branch .Lvm_b_join
.Lvm_b_old:
	s_waitcnt vmcnt(3)
	ds_write_b128 v210, v[114:117]
	s_waitcnt vmcnt(2)
	ds_write_b128 v211, v[118:121]
	s_waitcnt vmcnt(1)
	ds_write2_b64 v213, v[122:123], v[124:125] offset1:1
	s_waitcnt vmcnt(0)
	ds_write2_b64 v215, v[126:127], v[128:129] offset1:1
	s_cbranch_vccnz .LBB0_297
.Lvm_b_join:
	v_add_u32_e32 v0, s29, v209
	v_subrev_u32_e32 v0, 64, v0
	v_cvt_f32_i32_e32 v0, v0
	v_mul_f32_e32 v0, v208, v0
	ds_write_b32 v234, v0

; __device__ __forceinline__ float xhalf_sum(float v) { auto rr = __builtin_amdgcn_permlane32_swap(__float_as_uint(v), __float_as_uint(v), false, false); return __uint_as_float(rr[0]) + __uint_as_float(rr[1]); }
; template <int MODE> ...
;     ...
;     const float lt = xhalf_sum(lsum);
;     if (hi == 0) wsf[r32] = 1.0f / lt;
;     asm volatile("s_waitcnt lgkmcnt(0)" ::: "memory");
.LBB0_303:
	s_waitcnt vmcnt(0)
	v_mov_b32_e32 v0, v237
	s_nop 1
	v_permlane32_swap_b32_e32 v237, v0
	s_and_saveexec_b64 s[4:5], s[40:41]
	s_cbranch_execz .LBB0_305
	v_add_f32_e32 v0, v237, v0
	v_div_scale_f32 v66, s[6:7], v0, v0, 1.0
	v_rcp_f32_e32 v67, v66
	v_div_scale_f32 v68, vcc, 1.0, v0, 1.0
	v_fma_f32 v69, -v66, v67, 1.0
	v_fmac_f32_e32 v67, v69, v67
	v_mul_f32_e32 v69, v68, v67
	v_fma_f32 v70, -v66, v69, v68
	v_fmac_f32_e32 v69, v70, v67
	v_fma_f32 v66, -v66, v69, v68
	v_div_fmas_f32 v66, v66, v67, v69
	v_div_fixup_f32 v0, v66, v0, 1.0
	ds_write_b32 v217, v0
